# v43 + residual GEMMs (FFN-down, out-proj) traverse M-tiles in reverse order (pm -> 95-pm) so the most recently written activation tiles are consumed first
# speedup vs baseline: 1.0085x; 1.0085x over previous
;     __host__ __device__ bool next(int i, Unit& u) const {
;         const long L = (long)i * G + c; if (L >= nwg) return false;
;         int wgid = (int)L; { const int q = nwg / NXCD, r = nwg % NXCD, xcd = wgid % NXCD, off = wgid / NXCD; wgid = (xcd < r ? xcd * (q + 1) : r * (q + 1) + (xcd - r) * q) + off; }
;         const int nig = WGM * nN, gid = wgid / nig, fm = gid * WGM, gsz = (nM - fm) < WGM ? (nM - fm) : WGM;
;         u.pm = fm + ((wgid % nig) % gsz); u.pn = (wgid % nig) / gsz; return true;
.LBB0_160:
	v_mov_b32_e32 v20, v246
	s_cmpk_lt_i32 s23, 0x300
	s_cselect_b64 s[4:5], -1, 0
	s_cmpk_gt_i32 s23, 0x2ff
	v_readfirstlane_b32 s67, v20
	s_cbranch_scc1 .LBB0_162
	s_ashr_i32 s6, s23, 31
	s_lshr_b32 s6, s6, 29
	s_add_i32 s6, s23, s6
	s_ashr_i32 s7, s6, 3
	s_and_b32 s6, s6, -8
	s_sub_i32 s6, s23, s6
	s_cmp_lt_i32 s6, 0
	s_movk_i32 s8, 0x61
	s_cselect_b32 s8, s8, 0x60
	s_mul_i32 s6, s6, s8
	s_add_i32 s6, s6, s7
	s_ashr_i32 s7, s6, 31
	s_lshr_b32 s7, s7, 27
	s_add_i32 s7, s6, s7
	s_ashr_i32 s8, s7, 5
	s_and_b32 s7, s7, 0xffe0
	s_sub_i32 s6, s6, s7
	s_bfe_i32 s7, s6, 0x80000
	s_bfe_u32 s7, s7, 0x2000d
	s_add_i32 s7, s6, s7
	s_bfe_i32 s9, s7, 0x80000
	s_and_b32 s7, s7, 0xfc
	s_sub_i32 s6, s6, s7
	s_lshl_b32 s8, s8, 2
	s_sext_i32_i16 s9, s9
	s_sext_i32_i8 s6, s6
	s_add_i32 s66, s8, s6
	s_sub_i32 s66, 0x5f, s66
	s_ashr_i32 s83, s9, 2

;     __host__ __device__ bool next(int i, Unit& u) const {
;         const long L = (long)i * G + c; if (L >= nwg) return false;
;         int wgid = (int)L; { const int q = nwg / NXCD, r = nwg % NXCD, xcd = wgid % NXCD, off = wgid / NXCD; wgid = (xcd < r ? xcd * (q + 1) : r * (q + 1) + (xcd - r) * q) + off; }
;         const int nig = WGM * nN, gid = wgid / nig, fm = gid * WGM, gsz = (nM - fm) < WGM ? (nM - fm) : WGM;
;         u.pm = fm + ((wgid % nig) % gsz); u.pn = (wgid % nig) / gsz; return true;
.LBB0_168:
	s_add_i32 s82, s82, 1
	v_readlane_b32 s0, v252, 45
	s_mul_i32 s0, s82, s0
	s_mul_hi_u32 s1, s82, s16
	s_add_i32 s1, s1, s0
	s_mul_i32 s0, s82, s16
	s_add_u32 s4, s0, s23
	s_addc_u32 s5, s1, s39
	s_waitcnt lgkmcnt(0)
	v_mov_b64_e32 v[2:3], 0x300
	v_cmp_lt_i64_e64 s[0:1], s[4:5], v[2:3]
	v_mov_b64_e32 v[2:3], 0x2ff
	v_cmp_gt_i64_e32 vcc, s[4:5], v[2:3]
	s_cbranch_vccnz .LBB0_170
	s_ashr_i32 s5, s4, 31
	s_lshr_b32 s5, s5, 29
	s_add_i32 s5, s4, s5
	s_ashr_i32 s67, s5, 3
	s_and_b32 s5, s5, -8
	s_sub_i32 s4, s4, s5
	s_cmp_lt_i32 s4, 0
	s_movk_i32 s5, 0x61
	s_cselect_b32 s5, s5, 0x60
	s_mul_i32 s4, s4, s5
	s_add_i32 s4, s4, s67
	s_ashr_i32 s5, s4, 31
	s_lshr_b32 s5, s5, 27
	s_add_i32 s5, s4, s5
	s_ashr_i32 s67, s5, 5
	s_lshl_b32 s67, s67, 2
	s_sub_i32 s84, 0x60, s67
	s_min_i32 s85, s84, 4
	s_abs_i32 s84, s85
	v_cvt_f32_u32_e32 v2, s84
	s_sub_i32 s97, 0, s84
	s_andn2_b32 s5, s5, 31
	s_sub_i32 s4, s4, s5
	v_rcp_iflag_f32_e32 v2, v2
	s_abs_i32 s5, s4
	s_xor_b32 s96, s4, s85
	s_ashr_i32 s96, s96, 31
	v_mul_f32_e32 v2, 0x4f7ffffe, v2
	v_cvt_u32_f32_e32 v2, v2
	s_nop 0
	v_readfirstlane_b32 vcc_lo, v2
	s_mul_i32 s97, s97, vcc_lo
	s_mul_hi_u32 s97, vcc_lo, s97
	s_add_i32 vcc_lo, vcc_lo, s97
	s_mul_hi_u32 s97, s5, vcc_lo
	s_mul_i32 vcc_lo, s97, s84
	s_sub_i32 s5, s5, vcc_lo
	s_add_i32 vcc_hi, s97, 1
	s_sub_i32 vcc_lo, s5, s84
	s_cmp_ge_u32 s5, s84
	s_cselect_b32 s97, vcc_hi, s97
	s_cselect_b32 s5, vcc_lo, s5
	s_add_i32 vcc_lo, s97, 1
	s_cmp_ge_u32 s5, s84
	s_cselect_b32 s5, vcc_lo, s97
	s_xor_b32 s5, s5, s96
	s_sub_i32 s5, s5, s96
	s_mov_b32 s17, s5
	s_mul_i32 s5, s5, s85
	s_sub_i32 s4, s4, s5
	s_add_i32 s42, s67, s4
	s_sub_i32 s42, 0x5f, s42
